# grid-barrier spin back-off: s_sleep 4 instead of s_sleep 1 (byte-neutral)
# speedup vs baseline: 1.0019x; 1.0014x over previous
; __global__ void __launch_bounds__(512, 2) fwd_megakernel(Params p) {
;     ...
;   if (p.ws == nullptr) grid.sync();
.LBB0_12:
	s_sleep 4
	global_load_dword v3, v2, s[4:5] offset:32 sc1
	s_waitcnt vmcnt(0)
	v_and_b32_e32 v3, 0xffff0000, v3
	v_cmp_ne_u32_e32 vcc, v3, v1
	s_or_b64 s[6:7], vcc, s[6:7]
	s_andn2_b64 exec, exec, s[6:7]
	s_cbranch_execnz .LBB0_12

; DI unsigned xb_ld(unsigned* p) { return __hip_atomic_load(p, __ATOMIC_RELAXED, __HIP_MEMORY_SCOPE_AGENT); }
; DI void xcd_barrier_complete(unsigned* bar, unsigned x, unsigned& nloc, unsigned& nx) {
;     ...
;   for (;;) {
;     sum = 0u; cnt = 0u; mine = 0u;
; #pragma unroll
;     for (unsigned j = 0; j < 16; ++j) { const unsigned c = xb_ld(&bar[XB_XCNT(j)]); sum += c; cnt += (c > 0u) ? 1u : 0u; mine = (j == x) ? c : mine; }
;     if (sum == G) break;
;     __builtin_amdgcn_s_sleep(1);
;     if ((++sp & 255u) == 0u) { if (xb_ld(&bar[XB_TMO])) break; if (sp > XB_SPIN_CAP) { atomicAdd(&bar[XB_TMO], 1u); break; } }
.LBB0_115:
	v_readlane_b32 s4, v253, 12
	s_waitcnt lgkmcnt(0)
	v_readlane_b32 s2, v253, 32
	v_readlane_b32 s3, v253, 33
	s_nop 4
	global_load_dword v0, v17, s[2:3] sc1
	v_readlane_b32 s2, v253, 34
	v_readlane_b32 s3, v253, 35
	s_nop 4
	global_load_dword v1, v17, s[2:3] sc1
	v_readlane_b32 s2, v253, 36
	v_readlane_b32 s3, v253, 37
	s_nop 4
	global_load_dword v2, v17, s[2:3] sc1
	v_readlane_b32 s2, v253, 38
	v_readlane_b32 s3, v253, 39
	s_nop 4
	global_load_dword v3, v17, s[2:3] sc1
	v_readlane_b32 s2, v253, 40
	v_readlane_b32 s3, v253, 41
	s_nop 4
	global_load_dword v5, v17, s[2:3] sc1
	v_readlane_b32 s2, v253, 42
	v_readlane_b32 s3, v253, 43
	s_nop 4
	global_load_dword v6, v17, s[2:3] sc1
	v_readlane_b32 s2, v253, 44
	v_readlane_b32 s3, v253, 45
	s_nop 4
	global_load_dword v7, v17, s[2:3] sc1
	v_readlane_b32 s2, v253, 46
	v_readlane_b32 s3, v253, 47
	s_nop 4
	global_load_dword v8, v17, s[2:3] sc1
	v_readlane_b32 s2, v253, 48
	v_readlane_b32 s3, v253, 49
	s_nop 4
	global_load_dword v9, v17, s[2:3] sc1
	v_readlane_b32 s2, v253, 50
	v_readlane_b32 s3, v253, 51
	s_nop 4
	global_load_dword v10, v17, s[2:3] sc1
	v_readlane_b32 s2, v253, 52
	v_readlane_b32 s3, v253, 53
	s_nop 4
	global_load_dword v11, v17, s[2:3] sc1
	v_readlane_b32 s2, v253, 54
	v_readlane_b32 s3, v253, 55
	s_nop 4
	global_load_dword v12, v17, s[2:3] sc1
	v_readlane_b32 s2, v253, 56
	v_readlane_b32 s3, v253, 57
	s_nop 4
	global_load_dword v13, v17, s[2:3] sc1
	v_readlane_b32 s2, v253, 58
	v_readlane_b32 s3, v253, 59
	s_nop 4
	global_load_dword v14, v17, s[2:3] sc1
	v_readlane_b32 s2, v253, 60
	v_readlane_b32 s3, v253, 61
	s_nop 4
	global_load_dword v15, v17, s[2:3] sc1
	v_readlane_b32 s2, v253, 62
	v_readlane_b32 s3, v253, 63
	s_nop 4
	global_load_dword v16, v17, s[2:3] sc1
	s_mov_b64 s[2:3], -1
	s_waitcnt vmcnt(0)
	v_add_u32_e32 v18, v1, v0
	v_add_u32_e32 v18, v18, v2
	v_add_u32_e32 v18, v18, v3
	v_add_u32_e32 v18, v18, v5
	v_add_u32_e32 v18, v18, v6
	v_add_u32_e32 v18, v18, v7
	v_add_u32_e32 v18, v18, v8
	v_add_u32_e32 v18, v18, v9
	v_add_u32_e32 v18, v18, v10
	v_add_u32_e32 v18, v18, v11
	v_add_u32_e32 v18, v18, v12
	v_add_u32_e32 v18, v18, v13
	v_add_u32_e32 v18, v18, v14
	v_add_u32_e32 v18, v18, v15
	v_add_u32_e32 v18, v18, v16
	v_cmp_eq_u32_e32 vcc, s4, v18
	s_mov_b64 s[4:5], -1
	s_cbranch_vccnz .LBB0_114
	s_and_b32 s2, s8, 0xff
	s_cmp_eq_u32 s2, 0
	s_mov_b64 s[2:3], -1
	s_mov_b64 s[6:7], -1
	s_sleep 4
	s_cbranch_scc1 .LBB0_119
	s_and_b64 vcc, exec, s[6:7]
	s_cbranch_vccz .LBB0_114

; DI unsigned xb_ld(unsigned* p) { return __hip_atomic_load(p, __ATOMIC_RELAXED, __HIP_MEMORY_SCOPE_AGENT); }
; #define XB_SPIN(cond, bar) do { unsigned _sp = 0; while (cond) { __builtin_amdgcn_s_sleep(1); \
;     if ((++_sp & 255u) == 0u) { if (xb_ld(&(bar)[XB_TMO])) break; if (_sp > XB_SPIN_CAP) { atomicAdd(&(bar)[XB_TMO], 1u); break; } } } } while (0)
; DI void xcd_barrier(const XcdBarrier& b) {
;     ...
;       else XB_SPIN(xb_ld(&bar[XB_TOPGEN]) == tg, bar);
.LBB0_133:
	s_and_b32 s12, s16, 0xff
	s_mov_b64 s[10:11], -1
	s_cmp_lg_u32 s12, 0
	s_mov_b64 s[14:15], -1
	s_sleep 4
	s_cbranch_scc0 .LBB0_136
	s_and_b64 vcc, exec, s[14:15]
	s_cbranch_vccz .LBB0_132

; DI unsigned xb_ld(unsigned* p) { return __hip_atomic_load(p, __ATOMIC_RELAXED, __HIP_MEMORY_SCOPE_AGENT); }
; #define XB_SPIN(cond, bar) do { unsigned _sp = 0; while (cond) { __builtin_amdgcn_s_sleep(1); \
;     if ((++_sp & 255u) == 0u) { if (xb_ld(&(bar)[XB_TMO])) break; if (_sp > XB_SPIN_CAP) { atomicAdd(&(bar)[XB_TMO], 1u); break; } } } } while (0)
; DI void xcd_barrier(const XcdBarrier& b) {
;     ...
;       XB_SPIN(xb_ld(&bar[XB_XGEN(b.x)]) == gen, bar);
.LBB0_150:
	s_and_b32 s10, s16, 0xff
	s_cmp_lg_u32 s10, 0
	s_mov_b64 s[12:13], -1
	s_sleep 4
	s_cbranch_scc0 .LBB0_153
	s_mov_b64 s[14:15], -1
	s_and_b64 vcc, exec, s[12:13]
	s_cbranch_vccz .LBB0_149

; DI unsigned xb_ld(unsigned* p) { return __hip_atomic_load(p, __ATOMIC_RELAXED, __HIP_MEMORY_SCOPE_AGENT); }
; DI void xcd_barrier_complete(unsigned* bar, unsigned x, unsigned& nloc, unsigned& nx) {
;     ...
;   for (;;) {
;     sum = 0u; cnt = 0u; mine = 0u;
; #pragma unroll
;     for (unsigned j = 0; j < 16; ++j) { const unsigned c = xb_ld(&bar[XB_XCNT(j)]); sum += c; cnt += (c > 0u) ? 1u : 0u; mine = (j == x) ? c : mine; }
;     if (sum == G) break;
;     __builtin_amdgcn_s_sleep(1);
;     if ((++sp & 255u) == 0u) { if (xb_ld(&bar[XB_TMO])) break; if (sp > XB_SPIN_CAP) { atomicAdd(&bar[XB_TMO], 1u); break; } }
.LBB0_212:
	v_readlane_b32 s2, v253, 32
	v_readlane_b32 s3, v253, 33
	v_readlane_b32 s4, v253, 12
	s_nop 3
	global_load_dword v0, v1, s[2:3] sc1
	v_readlane_b32 s2, v253, 34
	v_readlane_b32 s3, v253, 35
	s_waitcnt lgkmcnt(0)
	s_nop 3
	global_load_dword v2, v1, s[2:3] sc1
	v_readlane_b32 s2, v253, 36
	v_readlane_b32 s3, v253, 37
	s_waitcnt vmcnt(0)
	v_add_u32_e32 v17, v2, v0
	s_nop 2
	global_load_dword v3, v1, s[2:3] sc1
	v_readlane_b32 s2, v253, 38
	v_readlane_b32 s3, v253, 39
	s_waitcnt vmcnt(0)
	v_add_u32_e32 v17, v17, v3
	s_nop 2
	global_load_dword v4, v1, s[2:3] sc1
	v_readlane_b32 s2, v253, 40
	v_readlane_b32 s3, v253, 41
	s_waitcnt vmcnt(0)
	v_add_u32_e32 v17, v17, v4
	s_nop 2
	global_load_dword v5, v1, s[2:3] sc1
	v_readlane_b32 s2, v253, 42
	v_readlane_b32 s3, v253, 43
	s_waitcnt vmcnt(0)
	v_add_u32_e32 v17, v17, v5
	s_nop 2
	global_load_dword v6, v1, s[2:3] sc1
	v_readlane_b32 s2, v253, 44
	v_readlane_b32 s3, v253, 45
	s_waitcnt vmcnt(0)
	v_add_u32_e32 v17, v17, v6
	s_nop 2
	global_load_dword v7, v1, s[2:3] sc1
	v_readlane_b32 s2, v253, 46
	v_readlane_b32 s3, v253, 47
	s_waitcnt vmcnt(0)
	v_add_u32_e32 v17, v17, v7
	s_nop 2
	global_load_dword v8, v1, s[2:3] sc1
	v_readlane_b32 s2, v253, 48
	v_readlane_b32 s3, v253, 49
	s_waitcnt vmcnt(0)
	v_add_u32_e32 v17, v17, v8
	s_nop 2
	global_load_dword v9, v1, s[2:3] sc1
	v_readlane_b32 s2, v253, 50
	v_readlane_b32 s3, v253, 51
	s_waitcnt vmcnt(0)
	v_add_u32_e32 v17, v17, v9
	s_nop 2
	global_load_dword v10, v1, s[2:3] sc1
	v_readlane_b32 s2, v253, 52
	v_readlane_b32 s3, v253, 53
	s_waitcnt vmcnt(0)
	v_add_u32_e32 v17, v17, v10
	s_nop 2
	global_load_dword v11, v1, s[2:3] sc1
	v_readlane_b32 s2, v253, 54
	v_readlane_b32 s3, v253, 55
	s_waitcnt vmcnt(0)
	v_add_u32_e32 v17, v17, v11
	s_nop 2
	global_load_dword v12, v1, s[2:3] sc1
	v_readlane_b32 s2, v253, 56
	v_readlane_b32 s3, v253, 57
	s_waitcnt vmcnt(0)
	v_add_u32_e32 v17, v17, v12
	s_nop 2
	global_load_dword v13, v1, s[2:3] sc1
	v_readlane_b32 s2, v253, 58
	v_readlane_b32 s3, v253, 59
	s_waitcnt vmcnt(0)
	v_add_u32_e32 v17, v17, v13
	s_nop 2
	global_load_dword v14, v1, s[2:3] sc1
	v_readlane_b32 s2, v253, 60
	v_readlane_b32 s3, v253, 61
	s_waitcnt vmcnt(0)
	v_add_u32_e32 v17, v17, v14
	s_nop 2
	global_load_dword v15, v1, s[2:3] sc1
	v_readlane_b32 s2, v253, 62
	v_readlane_b32 s3, v253, 63
	s_waitcnt vmcnt(0)
	v_add_u32_e32 v17, v17, v15
	s_nop 2
	global_load_dword v16, v1, s[2:3] sc1
	s_mov_b64 s[2:3], -1
	s_waitcnt vmcnt(0)
	v_add_u32_e32 v17, v17, v16
	v_cmp_eq_u32_e32 vcc, s4, v17
	s_mov_b64 s[4:5], -1
	s_cbranch_vccnz .LBB0_211
	s_and_b32 s2, s8, 0xff
	s_cmp_eq_u32 s2, 0
	s_mov_b64 s[2:3], -1
	s_mov_b64 s[6:7], -1
	s_sleep 4
	s_cbranch_scc1 .LBB0_216
	s_and_b64 vcc, exec, s[6:7]
	s_cbranch_vccz .LBB0_211

.LBB0_230:
	s_and_b32 s14, s13, 0xff
	s_mov_b64 s[10:11], -1
	s_cmp_lg_u32 s14, 0
	s_mov_b64 s[16:17], -1
	s_sleep 4
	s_cbranch_scc0 .LBB0_233
	s_and_b64 vcc, exec, s[16:17]
	s_cbranch_vccz .LBB0_229

; DI unsigned xb_ld(unsigned* p) { return __hip_atomic_load(p, __ATOMIC_RELAXED, __HIP_MEMORY_SCOPE_AGENT); }
; DI void xcd_barrier_complete(unsigned* bar, unsigned x, unsigned& nloc, unsigned& nx) {
;     ...
;   for (;;) {
;     sum = 0u; cnt = 0u; mine = 0u;
; #pragma unroll
;     for (unsigned j = 0; j < 16; ++j) { const unsigned c = xb_ld(&bar[XB_XCNT(j)]); sum += c; cnt += (c > 0u) ? 1u : 0u; mine = (j == x) ? c : mine; }
;     if (sum == G) break;
;     __builtin_amdgcn_s_sleep(1);
;     if ((++sp & 255u) == 0u) { if (xb_ld(&bar[XB_TMO])) break; if (sp > XB_SPIN_CAP) { atomicAdd(&bar[XB_TMO], 1u); break; } }
.LBB0_890:
	v_readlane_b32 s2, v253, 32
	v_readlane_b32 s3, v253, 33
	v_readlane_b32 s4, v253, 12
	s_nop 3
	global_load_dword v0, v1, s[2:3] sc1
	v_readlane_b32 s2, v253, 34
	v_readlane_b32 s3, v253, 35
	s_waitcnt lgkmcnt(0)
	s_nop 3
	global_load_dword v2, v1, s[2:3] sc1
	v_readlane_b32 s2, v253, 36
	v_readlane_b32 s3, v253, 37
	s_waitcnt vmcnt(0)
	v_add_u32_e32 v17, v2, v0
	s_nop 2
	global_load_dword v3, v1, s[2:3] sc1
	v_readlane_b32 s2, v253, 38
	v_readlane_b32 s3, v253, 39
	s_waitcnt vmcnt(0)
	v_add_u32_e32 v17, v17, v3
	s_nop 2
	global_load_dword v4, v1, s[2:3] sc1
	v_readlane_b32 s2, v253, 40
	v_readlane_b32 s3, v253, 41
	s_waitcnt vmcnt(0)
	v_add_u32_e32 v17, v17, v4
	s_nop 2
	global_load_dword v5, v1, s[2:3] sc1
	v_readlane_b32 s2, v253, 42
	v_readlane_b32 s3, v253, 43
	s_waitcnt vmcnt(0)
	v_add_u32_e32 v17, v17, v5
	s_nop 2
	global_load_dword v6, v1, s[2:3] sc1
	v_readlane_b32 s2, v253, 44
	v_readlane_b32 s3, v253, 45
	s_waitcnt vmcnt(0)
	v_add_u32_e32 v17, v17, v6
	s_nop 2
	global_load_dword v7, v1, s[2:3] sc1
	v_readlane_b32 s2, v253, 46
	v_readlane_b32 s3, v253, 47
	s_waitcnt vmcnt(0)
	v_add_u32_e32 v17, v17, v7
	s_nop 2
	global_load_dword v8, v1, s[2:3] sc1
	v_readlane_b32 s2, v253, 48
	v_readlane_b32 s3, v253, 49
	s_waitcnt vmcnt(0)
	v_add_u32_e32 v17, v17, v8
	s_nop 2
	global_load_dword v9, v1, s[2:3] sc1
	v_readlane_b32 s2, v253, 50
	v_readlane_b32 s3, v253, 51
	s_waitcnt vmcnt(0)
	v_add_u32_e32 v17, v17, v9
	s_nop 2
	global_load_dword v10, v1, s[2:3] sc1
	v_readlane_b32 s2, v253, 52
	v_readlane_b32 s3, v253, 53
	s_waitcnt vmcnt(0)
	v_add_u32_e32 v17, v17, v10
	s_nop 2
	global_load_dword v11, v1, s[2:3] sc1
	v_readlane_b32 s2, v253, 54
	v_readlane_b32 s3, v253, 55
	s_waitcnt vmcnt(0)
	v_add_u32_e32 v17, v17, v11
	s_nop 2
	global_load_dword v12, v1, s[2:3] sc1
	v_readlane_b32 s2, v253, 56
	v_readlane_b32 s3, v253, 57
	s_waitcnt vmcnt(0)
	v_add_u32_e32 v17, v17, v12
	s_nop 2
	global_load_dword v13, v1, s[2:3] sc1
	v_readlane_b32 s2, v253, 58
	v_readlane_b32 s3, v253, 59
	s_waitcnt vmcnt(0)
	v_add_u32_e32 v17, v17, v13
	s_nop 2
	global_load_dword v14, v1, s[2:3] sc1
	v_readlane_b32 s2, v253, 60
	v_readlane_b32 s3, v253, 61
	s_waitcnt vmcnt(0)
	v_add_u32_e32 v17, v17, v14
	s_nop 2
	global_load_dword v15, v1, s[2:3] sc1
	v_readlane_b32 s2, v253, 62
	v_readlane_b32 s3, v253, 63
	s_waitcnt vmcnt(0)
	v_add_u32_e32 v17, v17, v15
	s_nop 2
	global_load_dword v16, v1, s[2:3] sc1
	s_mov_b64 s[2:3], -1
	s_waitcnt vmcnt(0)
	v_add_u32_e32 v17, v17, v16
	v_cmp_eq_u32_e32 vcc, s4, v17
	s_mov_b64 s[4:5], -1
	s_cbranch_vccnz .LBB0_889
	s_and_b32 s2, s10, 0xff
	s_cmp_eq_u32 s2, 0
	s_mov_b64 s[2:3], -1
	s_mov_b64 s[8:9], -1
	s_sleep 4
	s_cbranch_scc1 .LBB0_894
	s_and_b64 vcc, exec, s[8:9]
	s_cbranch_vccz .LBB0_889

.LBB0_908:
	s_and_b32 s16, s13, 0xff
	s_mov_b64 s[14:15], -1
	s_cmp_lg_u32 s16, 0
	s_mov_b64 s[20:21], -1
	s_sleep 4
	s_cbranch_scc0 .LBB0_911
	s_and_b64 vcc, exec, s[20:21]
	s_cbranch_vccz .LBB0_907
